# weight transposition (P0 and in-projection slots): f32 weight loads marked nt as well
# speedup vs baseline: 1.0315x; 1.0219x over previous
; #define LAS __attribute__((address_space(3)))
; DI unsigned pk2(float a, float b) { f32x2 v = {a, b}; bf16v2 r = __builtin_convertvector(v, bf16v2); return __builtin_bit_cast(unsigned, r); }
; DI void p0_transpose_item(const float* W, int K, int N, bf16_t* WT, LAS float* scr, int item, int lane) {
;     const int nblk = N / 32, kb = item / nblk, nb = item % nblk, k0 = 128 * kb, n0 = 32 * nb;
;     const int n4 = lane & 7, kr = lane >> 3;
;     f32x4 v[16];
; #pragma unroll
;     for (int i = 0; i < 16; ++i) v[i] = *(const f32x4*)(W + (size_t)(k0 + kr + 8 * i) * N + n0 + 4 * n4);
; #pragma unroll
;     for (int i = 0; i < 16; ++i) { LAS float* d = scr + (kr + 8 * i) * 33 + 4 * n4; d[0] = v[i][0]; d[1] = v[i][1]; d[2] = v[i][2]; d[3] = v[i][3]; }
;     asm volatile("s_waitcnt lgkmcnt(0)" ::: "memory");
;     const int c = lane & 15;
; #pragma unroll
;     for (int j = 0; j < 8; ++j) { const int n = (lane >> 4) + 4 * j; const LAS float* s = scr + (8 * c) * 33 + n;
;         u32x4 o; o.x = pk2(s[0 * 33], s[1 * 33]); o.y = pk2(s[2 * 33], s[3 * 33]); o.z = pk2(s[4 * 33], s[5 * 33]); o.w = pk2(s[6 * 33], s[7 * 33]);
;         *(u32x4*)(WT + (size_t)(n0 + n) * K + k0 + 8 * c) = o; }
;     asm volatile("s_waitcnt lgkmcnt(0)" ::: "memory");
; }
; DI void phase_p0(const Params& p, LAS unsigned char* lds, int gw, int NGW, int wave, int lane) {
;     ...
;         { const int j = r / I_OUT; p0_transpose_item(p.w_out_b + (size_t)j * D * D, D, D, (bf16_t*)(p.ws + WS_W + j * WPAIR + WO_OUTB), scr, r % I_OUT, lane); }
.LBB0_17:
	s_cmpk_gt_i32 s64, 0x11ff
	s_mov_b64 s[16:17], -1
	s_cbranch_scc0 .LBB0_27
	s_cmpk_gt_u32 s64, 0x19ff
	s_cbranch_scc0 .LBB0_24
	s_cmpk_gt_u32 s64, 0x39ff
	s_cbranch_scc0 .LBB0_21
	s_add_i32 s8, s64, 0xffffc600
	s_lshr_b32 s8, s8, 10
	s_lshl_b64 s[16:17], s[8:9], 24
	s_waitcnt lgkmcnt(0)
	s_add_u32 s16, s86, s16
	s_addc_u32 s17, s87, s17
	s_mul_hi_u32 s18, s8, 0x4200000
	s_mul_i32 s8, s8, 0x4200000
	s_add_u32 s19, s94, s8
	s_addc_u32 s18, s95, s18
	s_and_b32 s8, s20, 0x7e0
	s_and_b32 s65, s1, 0x780
	s_lshl_b32 s66, s8, 2
	s_add_u32 s16, s16, s66
	v_or_b32_e32 v5, s65, v6
	s_addc_u32 s17, s17, 0
	v_lshl_add_u64 v[50:51], s[16:17], 0, v[2:3]
	v_lshlrev_b32_e32 v52, 13, v5
	v_mov_b32_e32 v53, v3
	v_lshl_add_u64 v[110:111], v[50:51], 0, v[52:53]
	v_add_co_u32_e32 v54, vcc, s22, v110
	s_lshl_b32 s16, s65, 1
	s_nop 0
	v_addc_co_u32_e32 v55, vcc, 0, v111, vcc
	v_add_co_u32_e32 v58, vcc, s23, v110
	global_load_dwordx4 v[50:53], v[110:111], off nt
	s_nop 0
	global_load_dwordx4 v[54:57], v[54:55], off nt
	v_addc_co_u32_e32 v59, vcc, 0, v111, vcc
	v_add_co_u32_e32 v62, vcc, s24, v110
	s_add_u32 s16, s19, s16
	s_nop 0
	v_addc_co_u32_e32 v63, vcc, 0, v111, vcc
	v_add_co_u32_e32 v66, vcc, s25, v110
	global_load_dwordx4 v[58:61], v[58:59], off nt
	s_nop 0
	global_load_dwordx4 v[62:65], v[62:63], off nt
	v_addc_co_u32_e32 v67, vcc, 0, v111, vcc
	v_add_co_u32_e32 v70, vcc, s26, v110
	s_addc_u32 s17, s18, 0
	s_nop 0
	v_addc_co_u32_e32 v71, vcc, 0, v111, vcc
	v_add_co_u32_e32 v74, vcc, s27, v110
	global_load_dwordx4 v[66:69], v[66:67], off nt
	s_nop 0
	global_load_dwordx4 v[70:73], v[70:71], off nt
	v_addc_co_u32_e32 v75, vcc, 0, v111, vcc
	v_add_co_u32_e32 v78, vcc, s28, v110
	v_mov_b32_e32 v5, v3
	s_nop 0
	v_addc_co_u32_e32 v79, vcc, 0, v111, vcc
	v_add_co_u32_e32 v82, vcc, s29, v110
	global_load_dwordx4 v[74:77], v[74:75], off nt
	s_nop 0
	global_load_dwordx4 v[78:81], v[78:79], off nt
	v_addc_co_u32_e32 v83, vcc, 0, v111, vcc
	v_add_co_u32_e32 v86, vcc, s30, v110
	s_nop 1
	v_addc_co_u32_e32 v87, vcc, 0, v111, vcc
	v_add_co_u32_e32 v90, vcc, s31, v110
	global_load_dwordx4 v[82:85], v[82:83], off nt
	s_nop 0
	global_load_dwordx4 v[86:89], v[86:87], off nt
	v_addc_co_u32_e32 v91, vcc, 0, v111, vcc
	v_add_co_u32_e32 v94, vcc, s33, v110
	s_nop 1
	v_addc_co_u32_e32 v95, vcc, 0, v111, vcc
	v_add_co_u32_e32 v98, vcc, s34, v110
	global_load_dwordx4 v[90:93], v[90:91], off nt
	s_nop 0
	global_load_dwordx4 v[94:97], v[94:95], off nt
	v_addc_co_u32_e32 v99, vcc, 0, v111, vcc
	v_add_co_u32_e32 v102, vcc, s35, v110
	s_nop 1
	v_addc_co_u32_e32 v103, vcc, 0, v111, vcc
	global_load_dwordx4 v[98:101], v[98:99], off nt
	s_nop 0
	global_load_dwordx4 v[102:105], v[102:103], off nt
	v_add_co_u32_e32 v106, vcc, s36, v110
	s_nop 1
	v_addc_co_u32_e32 v107, vcc, 0, v111, vcc
	global_load_dwordx4 v[106:109], v[106:107], off nt
	v_add_co_u32_e32 v110, vcc, s37, v110
	s_nop 1
	v_addc_co_u32_e32 v111, vcc, 0, v111, vcc
	global_load_dwordx4 v[110:113], v[110:111], off nt
	s_waitcnt vmcnt(15)
	ds_write2_b32 v7, v50, v51 offset1:1
	ds_write2_b32 v7, v52, v53 offset0:2 offset1:3
	s_waitcnt vmcnt(14)
	ds_write2_b32 v17, v54, v55 offset1:1
	ds_write2_b32 v18, v56, v57 offset1:1
	s_waitcnt vmcnt(13)
	ds_write2_b32 v19, v58, v59 offset1:1
	ds_write2_b32 v20, v60, v61 offset1:1
	s_waitcnt vmcnt(12)
	ds_write2_b32 v21, v62, v63 offset1:1
	ds_write2_b32 v22, v64, v65 offset1:1
	s_waitcnt vmcnt(11)
	ds_write2_b32 v23, v66, v67 offset1:1
	ds_write2_b32 v24, v68, v69 offset1:1
	s_waitcnt vmcnt(10)
	ds_write2_b32 v25, v70, v71 offset1:1
	ds_write2_b32 v26, v72, v73 offset1:1
	s_waitcnt vmcnt(9)
	ds_write2_b32 v27, v74, v75 offset1:1
	ds_write2_b32 v28, v76, v77 offset1:1
	s_waitcnt vmcnt(8)
	ds_write2_b32 v29, v78, v79 offset1:1
	ds_write2_b32 v30, v80, v81 offset1:1
	s_waitcnt vmcnt(7)
	ds_write2_b32 v31, v82, v83 offset1:1
	ds_write2_b32 v32, v84, v85 offset1:1
	s_waitcnt vmcnt(6)
	ds_write2_b32 v33, v86, v87 offset1:1
	ds_write2_b32 v35, v88, v89 offset1:1
	s_waitcnt vmcnt(5)
	ds_write2_b32 v36, v90, v91 offset1:1
	ds_write2_b32 v37, v92, v93 offset1:1
	s_waitcnt vmcnt(4)
	ds_write2_b32 v38, v94, v95 offset1:1
	ds_write2_b32 v39, v96, v97 offset1:1
	s_waitcnt vmcnt(3)
	ds_write2_b32 v40, v98, v99 offset1:1
	ds_write2_b32 v41, v100, v101 offset1:1
	s_waitcnt vmcnt(2)
	ds_write2_b32 v42, v102, v103 offset1:1
	ds_write2_b32 v43, v104, v105 offset1:1
	s_waitcnt vmcnt(1)
	ds_write2_b32 v44, v106, v107 offset1:1
	ds_write2_b32 v45, v108, v109 offset1:1
	s_waitcnt vmcnt(0)
	ds_write2_b32 v46, v110, v111 offset1:1
	ds_write2_b32 v47, v112, v113 offset1:1
	s_waitcnt lgkmcnt(0)
	ds_read2_b32 v[54:55], v9 offset0:33 offset1:37
	ds_read2_b32 v[56:57], v9 offset1:4
	ds_read2_b32 v[58:59], v9 offset0:66 offset1:70
	ds_read2_b32 v[60:61], v9 offset0:99 offset1:103
	ds_read2_b32 v[62:63], v9 offset0:132 offset1:136
	ds_read2_b32 v[64:65], v9 offset0:165 offset1:169
	ds_read2_b32 v[66:67], v9 offset0:198 offset1:202
	ds_read2_b32 v[68:69], v9 offset0:231 offset1:235
	v_lshl_add_u64 v[50:51], s[16:17], 0, v[4:5]
	v_or_b32_e32 v5, s8, v8
	v_lshl_add_u64 v[70:71], v[50:51], 0, s[10:11]
	v_lshlrev_b32_e32 v72, 12, v5
	v_mov_b32_e32 v73, v3
	s_waitcnt lgkmcnt(6)
	v_cvt_pk_bf16_f32 v50, v56, v54
	s_waitcnt lgkmcnt(4)
	v_cvt_pk_bf16_f32 v51, v58, v60
	s_waitcnt lgkmcnt(2)
	v_cvt_pk_bf16_f32 v52, v62, v64
	s_waitcnt lgkmcnt(0)
; #define LAS __attribute__((address_space(3)))
; DI unsigned pk2(float a, float b) { f32x2 v = {a, b}; bf16v2 r = __builtin_convertvector(v, bf16v2); return __builtin_bit_cast(unsigned, r); }
; DI void p0_transpose_item(const float* W, int K, int N, bf16_t* WT, LAS float* scr, int item, int lane) {
;     ...
;     for (int i = 0; i < 16; ++i) v[i] = *(const f32x4*)(W + (size_t)(k0 + kr + 8 * i) * N + n0 + 4 * n4);
; #pragma unroll
;     for (int i = 0; i < 16; ++i) { LAS float* d = scr + (kr + 8 * i) * 33 + 4 * n4; d[0] = v[i][0]; d[1] = v[i][1]; d[2] = v[i][2]; d[3] = v[i][3]; }
;     asm volatile("s_waitcnt lgkmcnt(0)" ::: "memory");
;     const int c = lane & 15;
; #pragma unroll
;     for (int j = 0; j < 8; ++j) { const int n = (lane >> 4) + 4 * j; const LAS float* s = scr + (8 * c) * 33 + n;
;         u32x4 o; o.x = pk2(s[0 * 33], s[1 * 33]); o.y = pk2(s[2 * 33], s[3 * 33]); o.z = pk2(s[4 * 33], s[5 * 33]); o.w = pk2(s[6 * 33], s[7 * 33]);
;         *(u32x4*)(WT + (size_t)(n0 + n) * K + k0 + 8 * c) = o; }
	v_cvt_pk_bf16_f32 v53, v66, v68
	v_lshl_add_u64 v[72:73], v[70:71], 0, v[72:73]
	global_store_dwordx4 v[72:73], v[50:53], off
	v_or_b32_e32 v5, s8, v10
	v_lshlrev_b32_e32 v54, 12, v5
	v_cvt_pk_bf16_f32 v50, v57, v55
	v_cvt_pk_bf16_f32 v51, v59, v61
	v_cvt_pk_bf16_f32 v52, v63, v65
	v_cvt_pk_bf16_f32 v53, v67, v69
	ds_read2_b32 v[56:57], v9 offset0:41 offset1:45
	ds_read2_b32 v[58:59], v9 offset0:8 offset1:12
	ds_read2_b32 v[60:61], v9 offset0:74 offset1:78
	ds_read2_b32 v[62:63], v9 offset0:107 offset1:111
	ds_read2_b32 v[64:65], v9 offset0:140 offset1:144
	ds_read2_b32 v[66:67], v9 offset0:173 offset1:177
	ds_read2_b32 v[68:69], v9 offset0:206 offset1:210
	ds_read2_b32 v[72:73], v9 offset0:239 offset1:243
	v_mov_b32_e32 v55, v3
	v_lshl_add_u64 v[54:55], v[70:71], 0, v[54:55]
	v_or_b32_e32 v5, s8, v11
	global_store_dwordx4 v[54:55], v[50:53], off
	v_lshlrev_b32_e32 v54, 12, v5
	v_mov_b32_e32 v55, v3
	s_waitcnt lgkmcnt(6)
	v_cvt_pk_bf16_f32 v50, v58, v56
	s_waitcnt lgkmcnt(4)
	v_cvt_pk_bf16_f32 v51, v60, v62
	s_waitcnt lgkmcnt(2)
	v_cvt_pk_bf16_f32 v52, v64, v66
	s_waitcnt lgkmcnt(0)
	v_cvt_pk_bf16_f32 v53, v68, v72
	v_lshl_add_u64 v[54:55], v[70:71], 0, v[54:55]
	global_store_dwordx4 v[54:55], v[50:53], off
	v_or_b32_e32 v5, s8, v12
	v_lshlrev_b32_e32 v54, 12, v5
	v_cvt_pk_bf16_f32 v50, v59, v57
	v_cvt_pk_bf16_f32 v51, v61, v63
	v_cvt_pk_bf16_f32 v52, v65, v67
	v_cvt_pk_bf16_f32 v53, v69, v73
	ds_read2_b32 v[56:57], v9 offset0:16 offset1:20
	ds_read2_b32 v[58:59], v9 offset0:49 offset1:53
	ds_read2_b32 v[60:61], v9 offset0:82 offset1:86
	ds_read2_b32 v[62:63], v9 offset0:115 offset1:119
	ds_read2_b32 v[64:65], v9 offset0:148 offset1:152
	ds_read2_b32 v[66:67], v9 offset0:181 offset1:185
	ds_read2_b32 v[68:69], v9 offset0:214 offset1:218
	ds_read2_b32 v[72:73], v9 offset0:247 offset1:251
	v_mov_b32_e32 v55, v3
	v_lshl_add_u64 v[54:55], v[70:71], 0, v[54:55]
	v_or_b32_e32 v5, s8, v13
	global_store_dwordx4 v[54:55], v[50:53], off
	v_lshlrev_b32_e32 v54, 12, v5
	v_mov_b32_e32 v55, v3
	s_waitcnt lgkmcnt(6)
	v_cvt_pk_bf16_f32 v50, v56, v58
	s_waitcnt lgkmcnt(4)
	v_cvt_pk_bf16_f32 v51, v60, v62
	s_waitcnt lgkmcnt(2)
	v_cvt_pk_bf16_f32 v52, v64, v66
	s_waitcnt lgkmcnt(0)
	v_cvt_pk_bf16_f32 v53, v68, v72
	v_lshl_add_u64 v[54:55], v[70:71], 0, v[54:55]
	global_store_dwordx4 v[54:55], v[50:53], off
	v_or_b32_e32 v5, s8, v14
	v_lshlrev_b32_e32 v54, 12, v5
	v_cvt_pk_bf16_f32 v50, v57, v59
	v_cvt_pk_bf16_f32 v51, v61, v63
	v_cvt_pk_bf16_f32 v52, v65, v67
	v_cvt_pk_bf16_f32 v53, v69, v73
	ds_read2_b32 v[56:57], v9 offset0:24 offset1:28
	ds_read2_b32 v[58:59], v9 offset0:57 offset1:61
	ds_read2_b32 v[60:61], v9 offset0:90 offset1:94
	ds_read2_b32 v[62:63], v9 offset0:123 offset1:127
	ds_read2_b32 v[64:65], v9 offset0:156 offset1:160
	ds_read2_b32 v[66:67], v9 offset0:189 offset1:193
	ds_read2_b32 v[68:69], v9 offset0:222 offset1:226
	ds_read2_b32 v[72:73], v48 offset0:127 offset1:131
	v_mov_b32_e32 v55, v3
	v_lshl_add_u64 v[54:55], v[70:71], 0, v[54:55]
	v_or_b32_e32 v5, s8, v15
	global_store_dwordx4 v[54:55], v[50:53], off
	v_lshlrev_b32_e32 v54, 12, v5
	v_mov_b32_e32 v55, v3
	s_waitcnt lgkmcnt(6)
	v_cvt_pk_bf16_f32 v50, v56, v58
	s_waitcnt lgkmcnt(4)
	v_cvt_pk_bf16_f32 v51, v60, v62
	s_waitcnt lgkmcnt(2)
	v_cvt_pk_bf16_f32 v52, v64, v66
	s_waitcnt lgkmcnt(0)
	v_cvt_pk_bf16_f32 v53, v68, v72
	v_lshl_add_u64 v[54:55], v[70:71], 0, v[54:55]
	v_or_b32_e32 v5, s8, v16
	global_store_dwordx4 v[54:55], v[50:53], off
	v_lshlrev_b32_e32 v54, 12, v5
	v_mov_b32_e32 v55, v3
	v_cvt_pk_bf16_f32 v50, v57, v59
	v_cvt_pk_bf16_f32 v51, v61, v63
	v_cvt_pk_bf16_f32 v52, v65, v67
	v_cvt_pk_bf16_f32 v53, v69, v73
	v_lshl_add_u64 v[54:55], v[70:71], 0, v[54:55]
	global_store_dwordx4 v[54:55], v[50:53], off
	s_waitcnt lgkmcnt(0)
	s_mov_b64 s[16:17], 0
.LBB0_21:
	s_andn2_b64 vcc, exec, s[16:17]
	s_cbranch_vccnz .LBB0_23
	s_add_i32 s18, s64, 0xffffe600
	s_lshr_b32 s8, s18, 12
	s_lshl_b64 s[16:17], s[8:9], 26
	s_waitcnt lgkmcnt(0)
	s_add_u32 s16, s84, s16
	s_addc_u32 s17, s85, s17
	s_mul_hi_u32 s19, s8, 0x4200000
	s_mul_i32 s8, s8, 0x4200000
	s_add_u32 s65, s94, s8
	s_addc_u32 s19, s95, s19
	s_lshr_b32 s8, s18, 1
	s_and_b32 s18, s8, 0x780
	s_and_b32 s8, s20, 0x1fe0
	s_lshl_b32 s66, s8, 2
	s_add_u32 s16, s16, s66
	v_or_b32_e32 v5, s18, v6
	s_addc_u32 s17, s17, 0
	v_lshl_add_u64 v[50:51], s[16:17], 0, v[2:3]
	v_lshlrev_b32_e32 v52, 15, v5
	v_mov_b32_e32 v53, v3
	v_lshl_add_u64 v[110:111], v[50:51], 0, v[52:53]
	v_add_co_u32_e32 v54, vcc, s25, v110
	s_lshl_b32 s16, s18, 1
	s_nop 0
	v_addc_co_u32_e32 v55, vcc, 0, v111, vcc
	v_add_co_u32_e32 v58, vcc, s29, v110
	global_load_dwordx4 v[50:53], v[110:111], off nt
	s_nop 0
	global_load_dwordx4 v[54:57], v[54:55], off nt
	v_addc_co_u32_e32 v59, vcc, 0, v111, vcc
	v_add_co_u32_e32 v62, vcc, s34, v110
	s_add_u32 s16, s65, s16
	s_nop 0
	v_addc_co_u32_e32 v63, vcc, 0, v111, vcc
	v_add_co_u32_e32 v66, vcc, s38, v110
	global_load_dwordx4 v[58:61], v[58:59], off nt
	s_nop 0
	global_load_dwordx4 v[62:65], v[62:63], off nt
	v_addc_co_u32_e32 v67, vcc, 0, v111, vcc
	v_add_co_u32_e32 v70, vcc, s39, v110
	s_addc_u32 s17, s19, 0
	s_nop 0
	v_addc_co_u32_e32 v71, vcc, 0, v111, vcc
	v_add_co_u32_e32 v74, vcc, s40, v110
	global_load_dwordx4 v[66:69], v[66:67], off nt
	s_nop 0
	global_load_dwordx4 v[70:73], v[70:71], off nt
	v_addc_co_u32_e32 v75, vcc, 0, v111, vcc
	v_add_co_u32_e32 v78, vcc, s41, v110
	v_mov_b32_e32 v5, v3
	s_nop 0
	v_addc_co_u32_e32 v79, vcc, 0, v111, vcc
	v_add_co_u32_e32 v82, vcc, s42, v110
	global_load_dwordx4 v[74:77], v[74:75], off nt
	s_nop 0
	global_load_dwordx4 v[78:81], v[78:79], off nt
	v_addc_co_u32_e32 v83, vcc, 0, v111, vcc
	v_add_co_u32_e32 v86, vcc, s43, v110
	s_nop 1
	v_addc_co_u32_e32 v87, vcc, 0, v111, vcc
	v_add_co_u32_e32 v90, vcc, s44, v110
	global_load_dwordx4 v[82:85], v[82:83], off nt
	s_nop 0
	global_load_dwordx4 v[86:89], v[86:87], off nt
	v_addc_co_u32_e32 v91, vcc, 0, v111, vcc
	v_add_co_u32_e32 v94, vcc, s45, v110
	s_nop 1
	v_addc_co_u32_e32 v95, vcc, 0, v111, vcc
	v_add_co_u32_e32 v98, vcc, s46, v110
	global_load_dwordx4 v[90:93], v[90:91], off nt
	s_nop 0
	global_load_dwordx4 v[94:97], v[94:95], off nt
	v_addc_co_u32_e32 v99, vcc, 0, v111, vcc
	v_add_co_u32_e32 v102, vcc, s47, v110
	s_nop 1
	v_addc_co_u32_e32 v103, vcc, 0, v111, vcc
	global_load_dwordx4 v[98:101], v[98:99], off nt
	s_nop 0
	global_load_dwordx4 v[102:105], v[102:103], off nt
	v_add_co_u32_e32 v106, vcc, s48, v110
	s_nop 1
	v_addc_co_u32_e32 v107, vcc, 0, v111, vcc
	global_load_dwordx4 v[106:109], v[106:107], off nt
	v_add_co_u32_e32 v110, vcc, s49, v110
	s_nop 1
	v_addc_co_u32_e32 v111, vcc, 0, v111, vcc
	global_load_dwordx4 v[110:113], v[110:111], off nt
	s_waitcnt vmcnt(15)
; #define LAS __attribute__((address_space(3)))
; DI unsigned pk2(float a, float b) { f32x2 v = {a, b}; bf16v2 r = __builtin_convertvector(v, bf16v2); return __builtin_bit_cast(unsigned, r); }
; DI void p0_transpose_item(const float* W, int K, int N, bf16_t* WT, LAS float* scr, int item, int lane) {
;     ...
;     for (int i = 0; i < 16; ++i) { LAS float* d = scr + (kr + 8 * i) * 33 + 4 * n4; d[0] = v[i][0]; d[1] = v[i][1]; d[2] = v[i][2]; d[3] = v[i][3]; }
;     asm volatile("s_waitcnt lgkmcnt(0)" ::: "memory");
;     const int c = lane & 15;
; #pragma unroll
;     for (int j = 0; j < 8; ++j) { const int n = (lane >> 4) + 4 * j; const LAS float* s = scr + (8 * c) * 33 + n;
;         u32x4 o; o.x = pk2(s[0 * 33], s[1 * 33]); o.y = pk2(s[2 * 33], s[3 * 33]); o.z = pk2(s[4 * 33], s[5 * 33]); o.w = pk2(s[6 * 33], s[7 * 33]);
;         *(u32x4*)(WT + (size_t)(n0 + n) * K + k0 + 8 * c) = o; }
;     asm volatile("s_waitcnt lgkmcnt(0)" ::: "memory");
	ds_write2_b32 v7, v50, v51 offset1:1
	ds_write2_b32 v7, v52, v53 offset0:2 offset1:3
	s_waitcnt vmcnt(14)
	ds_write2_b32 v17, v54, v55 offset1:1
	ds_write2_b32 v18, v56, v57 offset1:1
	s_waitcnt vmcnt(13)
	ds_write2_b32 v19, v58, v59 offset1:1
	ds_write2_b32 v20, v60, v61 offset1:1
	s_waitcnt vmcnt(12)
	ds_write2_b32 v21, v62, v63 offset1:1
	ds_write2_b32 v22, v64, v65 offset1:1
	s_waitcnt vmcnt(11)
	ds_write2_b32 v23, v66, v67 offset1:1
	ds_write2_b32 v24, v68, v69 offset1:1
	s_waitcnt vmcnt(10)
	ds_write2_b32 v25, v70, v71 offset1:1
	ds_write2_b32 v26, v72, v73 offset1:1
	s_waitcnt vmcnt(9)
	ds_write2_b32 v27, v74, v75 offset1:1
	ds_write2_b32 v28, v76, v77 offset1:1
	s_waitcnt vmcnt(8)
	ds_write2_b32 v29, v78, v79 offset1:1
	ds_write2_b32 v30, v80, v81 offset1:1
	s_waitcnt vmcnt(7)
	ds_write2_b32 v31, v82, v83 offset1:1
	ds_write2_b32 v32, v84, v85 offset1:1
	s_waitcnt vmcnt(6)
	ds_write2_b32 v33, v86, v87 offset1:1
	ds_write2_b32 v35, v88, v89 offset1:1
	s_waitcnt vmcnt(5)
	ds_write2_b32 v36, v90, v91 offset1:1
	ds_write2_b32 v37, v92, v93 offset1:1
	s_waitcnt vmcnt(4)
	ds_write2_b32 v38, v94, v95 offset1:1
	ds_write2_b32 v39, v96, v97 offset1:1
	s_waitcnt vmcnt(3)
	ds_write2_b32 v40, v98, v99 offset1:1
	ds_write2_b32 v41, v100, v101 offset1:1
	s_waitcnt vmcnt(2)
	ds_write2_b32 v42, v102, v103 offset1:1
	ds_write2_b32 v43, v104, v105 offset1:1
	s_waitcnt vmcnt(1)
	ds_write2_b32 v44, v106, v107 offset1:1
	ds_write2_b32 v45, v108, v109 offset1:1
	s_waitcnt vmcnt(0)
	ds_write2_b32 v46, v110, v111 offset1:1
	ds_write2_b32 v47, v112, v113 offset1:1
	s_waitcnt lgkmcnt(0)
	ds_read2_b32 v[54:55], v9 offset0:33 offset1:37
	ds_read2_b32 v[56:57], v9 offset1:4
	ds_read2_b32 v[58:59], v9 offset0:66 offset1:70
	ds_read2_b32 v[60:61], v9 offset0:99 offset1:103
	ds_read2_b32 v[62:63], v9 offset0:132 offset1:136
	ds_read2_b32 v[64:65], v9 offset0:165 offset1:169
	ds_read2_b32 v[66:67], v9 offset0:198 offset1:202
	ds_read2_b32 v[68:69], v9 offset0:231 offset1:235
	v_lshl_add_u64 v[50:51], s[16:17], 0, v[4:5]
	v_or_b32_e32 v5, s8, v8
	v_lshl_add_u64 v[70:71], v[50:51], 0, s[12:13]
	v_lshlrev_b32_e32 v72, 12, v5
	v_mov_b32_e32 v73, v3
	s_waitcnt lgkmcnt(6)
	v_cvt_pk_bf16_f32 v50, v56, v54
	s_waitcnt lgkmcnt(4)
	v_cvt_pk_bf16_f32 v51, v58, v60
	s_waitcnt lgkmcnt(2)
	v_cvt_pk_bf16_f32 v52, v62, v64
	s_waitcnt lgkmcnt(0)
	v_cvt_pk_bf16_f32 v53, v66, v68
	v_lshl_add_u64 v[72:73], v[70:71], 0, v[72:73]
	global_store_dwordx4 v[72:73], v[50:53], off
	v_or_b32_e32 v5, s8, v10
	v_lshlrev_b32_e32 v54, 12, v5
	v_cvt_pk_bf16_f32 v50, v57, v55
	v_cvt_pk_bf16_f32 v51, v59, v61
	v_cvt_pk_bf16_f32 v52, v63, v65
	v_cvt_pk_bf16_f32 v53, v67, v69
	ds_read2_b32 v[56:57], v9 offset0:41 offset1:45
	ds_read2_b32 v[58:59], v9 offset0:8 offset1:12
	ds_read2_b32 v[60:61], v9 offset0:74 offset1:78
	ds_read2_b32 v[62:63], v9 offset0:107 offset1:111
	ds_read2_b32 v[64:65], v9 offset0:140 offset1:144
	ds_read2_b32 v[66:67], v9 offset0:173 offset1:177
	ds_read2_b32 v[68:69], v9 offset0:206 offset1:210
	ds_read2_b32 v[72:73], v9 offset0:239 offset1:243
	v_mov_b32_e32 v55, v3
	v_lshl_add_u64 v[54:55], v[70:71], 0, v[54:55]
	v_or_b32_e32 v5, s8, v11
	global_store_dwordx4 v[54:55], v[50:53], off
	v_lshlrev_b32_e32 v54, 12, v5
	v_mov_b32_e32 v55, v3
	s_waitcnt lgkmcnt(6)
	v_cvt_pk_bf16_f32 v50, v58, v56
	s_waitcnt lgkmcnt(4)
	v_cvt_pk_bf16_f32 v51, v60, v62
	s_waitcnt lgkmcnt(2)
	v_cvt_pk_bf16_f32 v52, v64, v66
	s_waitcnt lgkmcnt(0)
	v_cvt_pk_bf16_f32 v53, v68, v72
	v_lshl_add_u64 v[54:55], v[70:71], 0, v[54:55]
	global_store_dwordx4 v[54:55], v[50:53], off
	v_or_b32_e32 v5, s8, v12
	v_lshlrev_b32_e32 v54, 12, v5
	v_cvt_pk_bf16_f32 v50, v59, v57
	v_cvt_pk_bf16_f32 v51, v61, v63
	v_cvt_pk_bf16_f32 v52, v65, v67
	v_cvt_pk_bf16_f32 v53, v69, v73
	ds_read2_b32 v[56:57], v9 offset0:16 offset1:20
	ds_read2_b32 v[58:59], v9 offset0:49 offset1:53
	ds_read2_b32 v[60:61], v9 offset0:82 offset1:86
	ds_read2_b32 v[62:63], v9 offset0:115 offset1:119
	ds_read2_b32 v[64:65], v9 offset0:148 offset1:152
	ds_read2_b32 v[66:67], v9 offset0:181 offset1:185
	ds_read2_b32 v[68:69], v9 offset0:214 offset1:218
	ds_read2_b32 v[72:73], v9 offset0:247 offset1:251
	v_mov_b32_e32 v55, v3
	v_lshl_add_u64 v[54:55], v[70:71], 0, v[54:55]
	v_or_b32_e32 v5, s8, v13
	global_store_dwordx4 v[54:55], v[50:53], off
	v_lshlrev_b32_e32 v54, 12, v5
	v_mov_b32_e32 v55, v3
	s_waitcnt lgkmcnt(6)
	v_cvt_pk_bf16_f32 v50, v56, v58
	s_waitcnt lgkmcnt(4)
	v_cvt_pk_bf16_f32 v51, v60, v62
	s_waitcnt lgkmcnt(2)
	v_cvt_pk_bf16_f32 v52, v64, v66
	s_waitcnt lgkmcnt(0)
	v_cvt_pk_bf16_f32 v53, v68, v72
	v_lshl_add_u64 v[54:55], v[70:71], 0, v[54:55]
	global_store_dwordx4 v[54:55], v[50:53], off
	v_or_b32_e32 v5, s8, v14
	v_lshlrev_b32_e32 v54, 12, v5
	v_cvt_pk_bf16_f32 v50, v57, v59
	v_cvt_pk_bf16_f32 v51, v61, v63
	v_cvt_pk_bf16_f32 v52, v65, v67
	v_cvt_pk_bf16_f32 v53, v69, v73
	ds_read2_b32 v[56:57], v9 offset0:24 offset1:28
	ds_read2_b32 v[58:59], v9 offset0:57 offset1:61
	ds_read2_b32 v[60:61], v9 offset0:90 offset1:94
	ds_read2_b32 v[62:63], v9 offset0:123 offset1:127
	ds_read2_b32 v[64:65], v9 offset0:156 offset1:160
	ds_read2_b32 v[66:67], v9 offset0:189 offset1:193
	ds_read2_b32 v[68:69], v9 offset0:222 offset1:226
	ds_read2_b32 v[72:73], v48 offset0:127 offset1:131
	v_mov_b32_e32 v55, v3
	v_lshl_add_u64 v[54:55], v[70:71], 0, v[54:55]
	v_or_b32_e32 v5, s8, v15
	global_store_dwordx4 v[54:55], v[50:53], off
	v_lshlrev_b32_e32 v54, 12, v5
	v_mov_b32_e32 v55, v3
	s_waitcnt lgkmcnt(6)
	v_cvt_pk_bf16_f32 v50, v56, v58
	s_waitcnt lgkmcnt(4)
	v_cvt_pk_bf16_f32 v51, v60, v62
	s_waitcnt lgkmcnt(2)
	v_cvt_pk_bf16_f32 v52, v64, v66
	s_waitcnt lgkmcnt(0)
	v_cvt_pk_bf16_f32 v53, v68, v72
	v_lshl_add_u64 v[54:55], v[70:71], 0, v[54:55]
	v_or_b32_e32 v5, s8, v16
	global_store_dwordx4 v[54:55], v[50:53], off
	v_lshlrev_b32_e32 v54, 12, v5
	v_mov_b32_e32 v55, v3
	v_cvt_pk_bf16_f32 v50, v57, v59
	v_cvt_pk_bf16_f32 v51, v61, v63
	v_cvt_pk_bf16_f32 v52, v65, v67
	v_cvt_pk_bf16_f32 v53, v69, v73
	v_lshl_add_u64 v[54:55], v[70:71], 0, v[54:55]
	global_store_dwordx4 v[54:55], v[50:53], off
	s_waitcnt lgkmcnt(0)

; #define LAS __attribute__((address_space(3)))
; DI void p0_transpose_item(const float* W, int K, int N, bf16_t* WT, LAS float* scr, int item, int lane) {
;     ...
;     for (int i = 0; i < 16; ++i) v[i] = *(const f32x4*)(W + (size_t)(k0 + kr + 8 * i) * N + n0 + 4 * n4);
; #pragma unroll
;     for (int i = 0; i < 16; ++i) { LAS float* d = scr + (kr + 8 * i) * 33 + 4 * n4; d[0] = v[i][0]; d[1] = v[i][1]; d[2] = v[i][2]; d[3] = v[i][3]; }
; DI void phase_p0(const Params& p, LAS unsigned char* lds, int gw, int NGW, int wave, int lane) {
;     ...
;         if (r < 2 * I_OUT) { const int j = r / I_OUT; p0_transpose_item(p.w_out_a + (size_t)j * D * D, D, D, (bf16_t*)(p.ws + WS_W + j * WPAIR + WO_OUTA), scr, r % I_OUT, lane); continue; } r -= 2 * I_OUT;
.LBB0_24:
	s_andn2_b64 vcc, exec, s[16:17]
	s_cbranch_vccnz .LBB0_26
	s_add_i32 s8, s64, 0xffffee00
	s_lshr_b32 s8, s8, 10
	s_lshl_b64 s[16:17], s[8:9], 24
	s_waitcnt lgkmcnt(0)
	s_add_u32 s16, s82, s16
	s_addc_u32 s17, s83, s17
	s_mul_hi_u32 s18, s8, 0x4200000
	s_mul_i32 s8, s8, 0x4200000
	s_add_u32 s19, s94, s8
	s_addc_u32 s18, s95, s18
	s_add_i32 s8, s1, 0x5000
	s_and_b32 s65, s8, 0x780
	s_and_b32 s8, s20, 0x7e0
	s_lshl_b32 s66, s8, 2
	s_add_u32 s16, s16, s66
	v_or_b32_e32 v5, s65, v6
	s_addc_u32 s17, s17, 0
	v_lshl_add_u64 v[50:51], s[16:17], 0, v[2:3]
	v_lshlrev_b32_e32 v52, 13, v5
	v_mov_b32_e32 v53, v3
	v_lshl_add_u64 v[110:111], v[50:51], 0, v[52:53]
	v_add_co_u32_e32 v54, vcc, s22, v110
	s_lshl_b32 s16, s65, 1
	s_nop 0
	v_addc_co_u32_e32 v55, vcc, 0, v111, vcc
	v_add_co_u32_e32 v58, vcc, s23, v110
	global_load_dwordx4 v[50:53], v[110:111], off nt
	s_nop 0
	global_load_dwordx4 v[54:57], v[54:55], off nt
	v_addc_co_u32_e32 v59, vcc, 0, v111, vcc
	v_add_co_u32_e32 v62, vcc, s24, v110
	s_add_u32 s16, s19, s16
	s_nop 0
	v_addc_co_u32_e32 v63, vcc, 0, v111, vcc
	v_add_co_u32_e32 v66, vcc, s25, v110
	global_load_dwordx4 v[58:61], v[58:59], off nt
	s_nop 0
	global_load_dwordx4 v[62:65], v[62:63], off nt
	v_addc_co_u32_e32 v67, vcc, 0, v111, vcc
	v_add_co_u32_e32 v70, vcc, s26, v110
	s_addc_u32 s17, s18, 0
	s_nop 0
	v_addc_co_u32_e32 v71, vcc, 0, v111, vcc
	v_add_co_u32_e32 v74, vcc, s27, v110
	global_load_dwordx4 v[66:69], v[66:67], off nt
	s_nop 0
	global_load_dwordx4 v[70:73], v[70:71], off nt
	v_addc_co_u32_e32 v75, vcc, 0, v111, vcc
	v_add_co_u32_e32 v78, vcc, s28, v110
	v_mov_b32_e32 v5, v3
	s_nop 0
	v_addc_co_u32_e32 v79, vcc, 0, v111, vcc
	v_add_co_u32_e32 v82, vcc, s29, v110
	global_load_dwordx4 v[74:77], v[74:75], off nt
	s_nop 0
	global_load_dwordx4 v[78:81], v[78:79], off nt
	v_addc_co_u32_e32 v83, vcc, 0, v111, vcc
	v_add_co_u32_e32 v86, vcc, s30, v110
	s_nop 1
	v_addc_co_u32_e32 v87, vcc, 0, v111, vcc
	v_add_co_u32_e32 v90, vcc, s31, v110
	global_load_dwordx4 v[82:85], v[82:83], off nt
	s_nop 0
	global_load_dwordx4 v[86:89], v[86:87], off nt
	v_addc_co_u32_e32 v91, vcc, 0, v111, vcc
	v_add_co_u32_e32 v94, vcc, s33, v110
	s_nop 1
	v_addc_co_u32_e32 v95, vcc, 0, v111, vcc
	v_add_co_u32_e32 v98, vcc, s34, v110
	global_load_dwordx4 v[90:93], v[90:91], off nt
	s_nop 0
	global_load_dwordx4 v[94:97], v[94:95], off nt
	v_addc_co_u32_e32 v99, vcc, 0, v111, vcc
	v_add_co_u32_e32 v102, vcc, s35, v110
	s_nop 1
	v_addc_co_u32_e32 v103, vcc, 0, v111, vcc
	global_load_dwordx4 v[98:101], v[98:99], off nt
	s_nop 0
	global_load_dwordx4 v[102:105], v[102:103], off nt
	v_add_co_u32_e32 v106, vcc, s36, v110
	s_nop 1
	v_addc_co_u32_e32 v107, vcc, 0, v111, vcc
	global_load_dwordx4 v[106:109], v[106:107], off nt
	v_add_co_u32_e32 v110, vcc, s37, v110
	s_nop 1
	v_addc_co_u32_e32 v111, vcc, 0, v111, vcc
	global_load_dwordx4 v[110:113], v[110:111], off nt
	s_waitcnt vmcnt(15)
	ds_write2_b32 v7, v50, v51 offset1:1
	ds_write2_b32 v7, v52, v53 offset0:2 offset1:3
	s_waitcnt vmcnt(14)
	ds_write2_b32 v17, v54, v55 offset1:1
	ds_write2_b32 v18, v56, v57 offset1:1
	s_waitcnt vmcnt(13)
	ds_write2_b32 v19, v58, v59 offset1:1
	ds_write2_b32 v20, v60, v61 offset1:1
	s_waitcnt vmcnt(12)
	ds_write2_b32 v21, v62, v63 offset1:1
	ds_write2_b32 v22, v64, v65 offset1:1
	s_waitcnt vmcnt(11)
	ds_write2_b32 v23, v66, v67 offset1:1
	ds_write2_b32 v24, v68, v69 offset1:1
	s_waitcnt vmcnt(10)
	ds_write2_b32 v25, v70, v71 offset1:1
	ds_write2_b32 v26, v72, v73 offset1:1
	s_waitcnt vmcnt(9)
	ds_write2_b32 v27, v74, v75 offset1:1
	ds_write2_b32 v28, v76, v77 offset1:1
	s_waitcnt vmcnt(8)
	ds_write2_b32 v29, v78, v79 offset1:1
	ds_write2_b32 v30, v80, v81 offset1:1
	s_waitcnt vmcnt(7)
	ds_write2_b32 v31, v82, v83 offset1:1
	ds_write2_b32 v32, v84, v85 offset1:1
	s_waitcnt vmcnt(6)
	ds_write2_b32 v33, v86, v87 offset1:1
	ds_write2_b32 v35, v88, v89 offset1:1
	s_waitcnt vmcnt(5)
	ds_write2_b32 v36, v90, v91 offset1:1
	ds_write2_b32 v37, v92, v93 offset1:1
	s_waitcnt vmcnt(4)
	ds_write2_b32 v38, v94, v95 offset1:1
	ds_write2_b32 v39, v96, v97 offset1:1
	s_waitcnt vmcnt(3)
	ds_write2_b32 v40, v98, v99 offset1:1
	ds_write2_b32 v41, v100, v101 offset1:1
	s_waitcnt vmcnt(2)
	ds_write2_b32 v42, v102, v103 offset1:1
	ds_write2_b32 v43, v104, v105 offset1:1
	s_waitcnt vmcnt(1)
	ds_write2_b32 v44, v106, v107 offset1:1
	ds_write2_b32 v45, v108, v109 offset1:1
	s_waitcnt vmcnt(0)
	ds_write2_b32 v46, v110, v111 offset1:1
	ds_write2_b32 v47, v112, v113 offset1:1
	s_waitcnt lgkmcnt(0)
; #define LAS __attribute__((address_space(3)))
; DI unsigned pk2(float a, float b) { f32x2 v = {a, b}; bf16v2 r = __builtin_convertvector(v, bf16v2); return __builtin_bit_cast(unsigned, r); }
; DI void p0_transpose_item(const float* W, int K, int N, bf16_t* WT, LAS float* scr, int item, int lane) {
;     ...
;     const int c = lane & 15;
; #pragma unroll
;     for (int j = 0; j < 8; ++j) { const int n = (lane >> 4) + 4 * j; const LAS float* s = scr + (8 * c) * 33 + n;
;         u32x4 o; o.x = pk2(s[0 * 33], s[1 * 33]); o.y = pk2(s[2 * 33], s[3 * 33]); o.z = pk2(s[4 * 33], s[5 * 33]); o.w = pk2(s[6 * 33], s[7 * 33]);
;         *(u32x4*)(WT + (size_t)(n0 + n) * K + k0 + 8 * c) = o; }
;     asm volatile("s_waitcnt lgkmcnt(0)" ::: "memory");
	ds_read2_b32 v[54:55], v9 offset0:33 offset1:37
	ds_read2_b32 v[56:57], v9 offset1:4
	ds_read2_b32 v[58:59], v9 offset0:66 offset1:70
	ds_read2_b32 v[60:61], v9 offset0:99 offset1:103
	ds_read2_b32 v[62:63], v9 offset0:132 offset1:136
	ds_read2_b32 v[64:65], v9 offset0:165 offset1:169
	ds_read2_b32 v[66:67], v9 offset0:198 offset1:202
	ds_read2_b32 v[68:69], v9 offset0:231 offset1:235
	v_lshl_add_u64 v[50:51], s[16:17], 0, v[4:5]
	v_or_b32_e32 v5, s8, v8
	v_lshl_add_u64 v[70:71], v[50:51], 0, s[14:15]
	v_lshlrev_b32_e32 v72, 12, v5
	v_mov_b32_e32 v73, v3
	s_waitcnt lgkmcnt(6)
	v_cvt_pk_bf16_f32 v50, v56, v54
	s_waitcnt lgkmcnt(4)
	v_cvt_pk_bf16_f32 v51, v58, v60
	s_waitcnt lgkmcnt(2)
	v_cvt_pk_bf16_f32 v52, v62, v64
	s_waitcnt lgkmcnt(0)
	v_cvt_pk_bf16_f32 v53, v66, v68
	v_lshl_add_u64 v[72:73], v[70:71], 0, v[72:73]
	global_store_dwordx4 v[72:73], v[50:53], off
	v_or_b32_e32 v5, s8, v10
	v_lshlrev_b32_e32 v54, 12, v5
	v_cvt_pk_bf16_f32 v50, v57, v55
	v_cvt_pk_bf16_f32 v51, v59, v61
	v_cvt_pk_bf16_f32 v52, v63, v65
	v_cvt_pk_bf16_f32 v53, v67, v69
	ds_read2_b32 v[56:57], v9 offset0:41 offset1:45
	ds_read2_b32 v[58:59], v9 offset0:8 offset1:12
	ds_read2_b32 v[60:61], v9 offset0:74 offset1:78
	ds_read2_b32 v[62:63], v9 offset0:107 offset1:111
	ds_read2_b32 v[64:65], v9 offset0:140 offset1:144
	ds_read2_b32 v[66:67], v9 offset0:173 offset1:177
	ds_read2_b32 v[68:69], v9 offset0:206 offset1:210
	ds_read2_b32 v[72:73], v9 offset0:239 offset1:243
	v_mov_b32_e32 v55, v3
	v_lshl_add_u64 v[54:55], v[70:71], 0, v[54:55]
	v_or_b32_e32 v5, s8, v11
	global_store_dwordx4 v[54:55], v[50:53], off
	v_lshlrev_b32_e32 v54, 12, v5
	v_mov_b32_e32 v55, v3
	s_waitcnt lgkmcnt(6)
	v_cvt_pk_bf16_f32 v50, v58, v56
	s_waitcnt lgkmcnt(4)
	v_cvt_pk_bf16_f32 v51, v60, v62
	s_waitcnt lgkmcnt(2)
	v_cvt_pk_bf16_f32 v52, v64, v66
	s_waitcnt lgkmcnt(0)
	v_cvt_pk_bf16_f32 v53, v68, v72
	v_lshl_add_u64 v[54:55], v[70:71], 0, v[54:55]
	global_store_dwordx4 v[54:55], v[50:53], off
	v_or_b32_e32 v5, s8, v12
	v_lshlrev_b32_e32 v54, 12, v5
	v_cvt_pk_bf16_f32 v50, v59, v57
	v_cvt_pk_bf16_f32 v51, v61, v63
	v_cvt_pk_bf16_f32 v52, v65, v67
	v_cvt_pk_bf16_f32 v53, v69, v73
	ds_read2_b32 v[56:57], v9 offset0:16 offset1:20
	ds_read2_b32 v[58:59], v9 offset0:49 offset1:53
	ds_read2_b32 v[60:61], v9 offset0:82 offset1:86
	ds_read2_b32 v[62:63], v9 offset0:115 offset1:119
	ds_read2_b32 v[64:65], v9 offset0:148 offset1:152
	ds_read2_b32 v[66:67], v9 offset0:181 offset1:185
	ds_read2_b32 v[68:69], v9 offset0:214 offset1:218
	ds_read2_b32 v[72:73], v9 offset0:247 offset1:251
	v_mov_b32_e32 v55, v3
	v_lshl_add_u64 v[54:55], v[70:71], 0, v[54:55]
	v_or_b32_e32 v5, s8, v13
	global_store_dwordx4 v[54:55], v[50:53], off
	v_lshlrev_b32_e32 v54, 12, v5
	v_mov_b32_e32 v55, v3
	s_waitcnt lgkmcnt(6)
	v_cvt_pk_bf16_f32 v50, v56, v58
	s_waitcnt lgkmcnt(4)
	v_cvt_pk_bf16_f32 v51, v60, v62
	s_waitcnt lgkmcnt(2)
	v_cvt_pk_bf16_f32 v52, v64, v66
	s_waitcnt lgkmcnt(0)
	v_cvt_pk_bf16_f32 v53, v68, v72
	v_lshl_add_u64 v[54:55], v[70:71], 0, v[54:55]
	global_store_dwordx4 v[54:55], v[50:53], off
	v_or_b32_e32 v5, s8, v14
	v_lshlrev_b32_e32 v54, 12, v5
	v_cvt_pk_bf16_f32 v50, v57, v59
	v_cvt_pk_bf16_f32 v51, v61, v63
	v_cvt_pk_bf16_f32 v52, v65, v67
	v_cvt_pk_bf16_f32 v53, v69, v73
	ds_read2_b32 v[56:57], v9 offset0:24 offset1:28
	ds_read2_b32 v[58:59], v9 offset0:57 offset1:61
	ds_read2_b32 v[60:61], v9 offset0:90 offset1:94
	ds_read2_b32 v[62:63], v9 offset0:123 offset1:127
	ds_read2_b32 v[64:65], v9 offset0:156 offset1:160
	ds_read2_b32 v[66:67], v9 offset0:189 offset1:193
	ds_read2_b32 v[68:69], v9 offset0:222 offset1:226
	ds_read2_b32 v[72:73], v48 offset0:127 offset1:131
	v_mov_b32_e32 v55, v3
	v_lshl_add_u64 v[54:55], v[70:71], 0, v[54:55]
	v_or_b32_e32 v5, s8, v15
	global_store_dwordx4 v[54:55], v[50:53], off
	v_lshlrev_b32_e32 v54, 12, v5
	v_mov_b32_e32 v55, v3
	s_waitcnt lgkmcnt(6)
	v_cvt_pk_bf16_f32 v50, v56, v58
	s_waitcnt lgkmcnt(4)
	v_cvt_pk_bf16_f32 v51, v60, v62
	s_waitcnt lgkmcnt(2)
	v_cvt_pk_bf16_f32 v52, v64, v66
	s_waitcnt lgkmcnt(0)
	v_cvt_pk_bf16_f32 v53, v68, v72
	v_lshl_add_u64 v[54:55], v[70:71], 0, v[54:55]
	v_or_b32_e32 v5, s8, v16
	global_store_dwordx4 v[54:55], v[50:53], off
	v_lshlrev_b32_e32 v54, 12, v5
	v_mov_b32_e32 v55, v3
	v_cvt_pk_bf16_f32 v50, v57, v59
	v_cvt_pk_bf16_f32 v51, v61, v63
	v_cvt_pk_bf16_f32 v52, v65, v67
	v_cvt_pk_bf16_f32 v53, v69, v73
	v_lshl_add_u64 v[54:55], v[70:71], 0, v[54:55]
	global_store_dwordx4 v[54:55], v[50:53], off
	s_waitcnt lgkmcnt(0)

; #define LAS __attribute__((address_space(3)))
; DI void p0_transpose_item(const float* W, int K, int N, bf16_t* WT, LAS float* scr, int item, int lane) {
;     ...
;     for (int i = 0; i < 16; ++i) v[i] = *(const f32x4*)(W + (size_t)(k0 + kr + 8 * i) * N + n0 + 4 * n4);
; #pragma unroll
;     for (int i = 0; i < 16; ++i) { LAS float* d = scr + (kr + 8 * i) * 33 + 4 * n4; d[0] = v[i][0]; d[1] = v[i][1]; d[2] = v[i][2]; d[3] = v[i][3]; }
; DI void phase_p0(const Params& p, LAS unsigned char* lds, int gw, int NGW, int wave, int lane) {
;     ...
;         if (r < 2 * I_INA) { const int j = r / I_INA; p0_transpose_item(p.w_in_a + (size_t)j * D * NA, D, NA, (bf16_t*)(p.ws + WS_W + j * WPAIR + WO_INA), scr, r % I_INA, lane); continue; } r -= 2 * I_INA;
.LBB0_27:
	s_andn2_b64 vcc, exec, s[16:17]
	s_cbranch_vccnz .LBB0_16
	s_mul_hi_i32 s8, s64, 0x38e38e39
	s_lshr_b32 s16, s8, 31
	s_ashr_i32 s8, s8, 9
	s_add_i32 s16, s8, s16
	s_mul_i32 s17, s16, 0x2400000
	s_mul_hi_i32 s8, s16, 0x2400000
	s_waitcnt lgkmcnt(0)
	s_add_u32 s19, s78, s17
	s_addc_u32 s68, s79, s8
	s_mul_i32 s8, s16, 0x4200000
	s_mul_hi_i32 s17, s16, 0x4200000
	s_add_u32 s8, s94, s8
	s_mulk_i32 s16, 0xf700
	s_addc_u32 s65, s95, s17
	s_add_i32 s16, s64, s16
	s_mul_i32 s17, s16, 0xe39
	s_lshr_b32 s18, s17, 31
	s_ashr_i32 s17, s17, 19
	s_add_i32 s17, s17, s18
	s_sext_i32_i16 s18, s17
	s_mulk_i32 s17, 0x90
	s_sub_i32 s16, s16, s17
	s_sext_i32_i16 s16, s16
	s_lshl_b32 s16, s16, 5
	s_ashr_i32 s17, s16, 31
	s_lshl_b32 s18, s18, 7
	s_lshl_b64 s[66:67], s[16:17], 2
	v_or_b32_e32 v5, s18, v6
	s_add_u32 s66, s19, s66
	s_addc_u32 s67, s68, s67
	v_mul_i32_i24_e32 v52, 0x1200, v5
	v_lshl_add_u64 v[50:51], s[66:67], 0, v[2:3]
	v_ashrrev_i32_e32 v53, 31, v52
	v_lshl_add_u64 v[110:111], v[52:53], 2, v[50:51]
	v_add_co_u32_e32 v54, vcc, s50, v110
	s_ashr_i32 s19, s18, 31
	s_nop 0
	v_addc_co_u32_e32 v55, vcc, 0, v111, vcc
	v_add_co_u32_e32 v58, vcc, s51, v110
	global_load_dwordx4 v[50:53], v[110:111], off nt
	s_nop 0
	global_load_dwordx4 v[54:57], v[54:55], off nt
	v_addc_co_u32_e32 v59, vcc, 0, v111, vcc
	v_add_co_u32_e32 v62, vcc, s52, v110
	s_lshl_b64 s[18:19], s[18:19], 1
	s_nop 0
	v_addc_co_u32_e32 v63, vcc, 0, v111, vcc
	v_add_co_u32_e32 v66, vcc, s30, v110
	global_load_dwordx4 v[58:61], v[58:59], off nt
	s_nop 0
	global_load_dwordx4 v[62:65], v[62:63], off nt
	v_addc_co_u32_e32 v67, vcc, 0, v111, vcc
	v_add_co_u32_e32 v70, vcc, s53, v110
	s_add_u32 s18, s8, s18
	s_nop 0
	v_addc_co_u32_e32 v71, vcc, 0, v111, vcc
	v_add_co_u32_e32 v74, vcc, s54, v110
	global_load_dwordx4 v[66:69], v[66:67], off nt
	s_nop 0
	global_load_dwordx4 v[70:73], v[70:71], off nt
	v_addc_co_u32_e32 v75, vcc, 0, v111, vcc
	v_add_co_u32_e32 v78, vcc, s55, v110
	s_addc_u32 s19, s65, s19
	s_nop 0
	v_addc_co_u32_e32 v79, vcc, 0, v111, vcc
	v_add_co_u32_e32 v82, vcc, s56, v110
	global_load_dwordx4 v[74:77], v[74:75], off nt
	s_nop 0
	global_load_dwordx4 v[78:81], v[78:79], off nt
	v_addc_co_u32_e32 v83, vcc, 0, v111, vcc
	v_add_co_u32_e32 v86, vcc, s57, v110
	v_mov_b32_e32 v5, v3
	s_nop 0
	v_addc_co_u32_e32 v87, vcc, 0, v111, vcc
	v_add_co_u32_e32 v90, vcc, s58, v110
	global_load_dwordx4 v[82:85], v[82:83], off nt
	s_nop 0
	global_load_dwordx4 v[86:89], v[86:87], off nt
	v_addc_co_u32_e32 v91, vcc, 0, v111, vcc
	v_add_co_u32_e32 v94, vcc, s59, v110
	s_nop 1
	v_addc_co_u32_e32 v95, vcc, 0, v111, vcc
	v_add_co_u32_e32 v98, vcc, s60, v110
	global_load_dwordx4 v[90:93], v[90:91], off nt
	s_nop 0
	global_load_dwordx4 v[94:97], v[94:95], off nt
	v_addc_co_u32_e32 v99, vcc, 0, v111, vcc
	v_add_co_u32_e32 v102, vcc, s61, v110
	s_nop 1
	v_addc_co_u32_e32 v103, vcc, 0, v111, vcc
	global_load_dwordx4 v[98:101], v[98:99], off nt
	s_nop 0
	global_load_dwordx4 v[102:105], v[102:103], off nt
	v_add_co_u32_e32 v106, vcc, s62, v110
	s_nop 1
	v_addc_co_u32_e32 v107, vcc, 0, v111, vcc
	global_load_dwordx4 v[106:109], v[106:107], off nt
	v_add_co_u32_e32 v110, vcc, s63, v110
	s_nop 1
	v_addc_co_u32_e32 v111, vcc, 0, v111, vcc
	global_load_dwordx4 v[110:113], v[110:111], off nt
	s_waitcnt vmcnt(15)
	ds_write2_b32 v7, v50, v51 offset1:1
	ds_write2_b32 v7, v52, v53 offset0:2 offset1:3
	s_waitcnt vmcnt(14)
	ds_write2_b32 v17, v54, v55 offset1:1
	ds_write2_b32 v18, v56, v57 offset1:1
	s_waitcnt vmcnt(13)
	ds_write2_b32 v19, v58, v59 offset1:1
	ds_write2_b32 v20, v60, v61 offset1:1
	s_waitcnt vmcnt(12)
	ds_write2_b32 v21, v62, v63 offset1:1
	ds_write2_b32 v22, v64, v65 offset1:1
	s_waitcnt vmcnt(11)
	ds_write2_b32 v23, v66, v67 offset1:1
	ds_write2_b32 v24, v68, v69 offset1:1
	s_waitcnt vmcnt(10)
	ds_write2_b32 v25, v70, v71 offset1:1
	ds_write2_b32 v26, v72, v73 offset1:1
	s_waitcnt vmcnt(9)
	ds_write2_b32 v27, v74, v75 offset1:1
	ds_write2_b32 v28, v76, v77 offset1:1
	s_waitcnt vmcnt(8)
	ds_write2_b32 v29, v78, v79 offset1:1
	ds_write2_b32 v30, v80, v81 offset1:1
	s_waitcnt vmcnt(7)
	ds_write2_b32 v31, v82, v83 offset1:1
	ds_write2_b32 v32, v84, v85 offset1:1
	s_waitcnt vmcnt(6)
	ds_write2_b32 v33, v86, v87 offset1:1
	ds_write2_b32 v35, v88, v89 offset1:1
	s_waitcnt vmcnt(5)
	ds_write2_b32 v36, v90, v91 offset1:1
	ds_write2_b32 v37, v92, v93 offset1:1
	s_waitcnt vmcnt(4)
	ds_write2_b32 v38, v94, v95 offset1:1
	ds_write2_b32 v39, v96, v97 offset1:1
	s_waitcnt vmcnt(3)
	ds_write2_b32 v40, v98, v99 offset1:1
	ds_write2_b32 v41, v100, v101 offset1:1
	s_waitcnt vmcnt(2)
	ds_write2_b32 v42, v102, v103 offset1:1
	ds_write2_b32 v43, v104, v105 offset1:1
	s_waitcnt vmcnt(1)
	ds_write2_b32 v44, v106, v107 offset1:1
	ds_write2_b32 v45, v108, v109 offset1:1
	s_waitcnt vmcnt(0)
; #define LAS __attribute__((address_space(3)))
; DI unsigned pk2(float a, float b) { f32x2 v = {a, b}; bf16v2 r = __builtin_convertvector(v, bf16v2); return __builtin_bit_cast(unsigned, r); }
; DI void p0_transpose_item(const float* W, int K, int N, bf16_t* WT, LAS float* scr, int item, int lane) {
;     ...
;     const int c = lane & 15;
; #pragma unroll
;     for (int j = 0; j < 8; ++j) { const int n = (lane >> 4) + 4 * j; const LAS float* s = scr + (8 * c) * 33 + n;
;         u32x4 o; o.x = pk2(s[0 * 33], s[1 * 33]); o.y = pk2(s[2 * 33], s[3 * 33]); o.z = pk2(s[4 * 33], s[5 * 33]); o.w = pk2(s[6 * 33], s[7 * 33]);
;         *(u32x4*)(WT + (size_t)(n0 + n) * K + k0 + 8 * c) = o; }
;     asm volatile("s_waitcnt lgkmcnt(0)" ::: "memory");
	ds_write2_b32 v46, v110, v111 offset1:1
	ds_write2_b32 v47, v112, v113 offset1:1
	s_waitcnt lgkmcnt(0)
	ds_read2_b32 v[54:55], v9 offset0:33 offset1:37
	ds_read2_b32 v[56:57], v9 offset1:4
	ds_read2_b32 v[58:59], v9 offset0:66 offset1:70
	ds_read2_b32 v[60:61], v9 offset0:99 offset1:103
	ds_read2_b32 v[62:63], v9 offset0:132 offset1:136
	ds_read2_b32 v[64:65], v9 offset0:165 offset1:169
	ds_read2_b32 v[66:67], v9 offset0:198 offset1:202
	ds_read2_b32 v[68:69], v9 offset0:231 offset1:235
	v_or_b32_e32 v70, s16, v8
	v_ashrrev_i32_e32 v71, 31, v70
	v_lshlrev_b64 v[70:71], 12, v[70:71]
	v_lshl_add_u64 v[72:73], s[18:19], 0, v[4:5]
	s_waitcnt lgkmcnt(6)
	v_cvt_pk_bf16_f32 v50, v56, v54
	s_waitcnt lgkmcnt(4)
	v_cvt_pk_bf16_f32 v51, v58, v60
	s_waitcnt lgkmcnt(2)
	v_cvt_pk_bf16_f32 v52, v62, v64
	s_waitcnt lgkmcnt(0)
	v_cvt_pk_bf16_f32 v53, v66, v68
	v_lshl_add_u64 v[70:71], v[72:73], 0, v[70:71]
	v_or_b32_e32 v54, s16, v10
	global_store_dwordx4 v[70:71], v[50:53], off
	s_nop 1
	v_cvt_pk_bf16_f32 v50, v57, v55
	v_ashrrev_i32_e32 v55, 31, v54
	v_cvt_pk_bf16_f32 v51, v59, v61
	v_cvt_pk_bf16_f32 v52, v63, v65
	v_cvt_pk_bf16_f32 v53, v67, v69
	v_lshlrev_b64 v[54:55], 12, v[54:55]
	ds_read2_b32 v[56:57], v9 offset0:41 offset1:45
	ds_read2_b32 v[58:59], v9 offset0:8 offset1:12
	ds_read2_b32 v[60:61], v9 offset0:74 offset1:78
	ds_read2_b32 v[62:63], v9 offset0:107 offset1:111
	ds_read2_b32 v[64:65], v9 offset0:140 offset1:144
	ds_read2_b32 v[66:67], v9 offset0:173 offset1:177
	ds_read2_b32 v[68:69], v9 offset0:206 offset1:210
	ds_read2_b32 v[70:71], v9 offset0:239 offset1:243
	v_lshl_add_u64 v[54:55], v[72:73], 0, v[54:55]
	global_store_dwordx4 v[54:55], v[50:53], off
	v_or_b32_e32 v54, s16, v11
	v_ashrrev_i32_e32 v55, 31, v54
	v_lshlrev_b64 v[54:55], 12, v[54:55]
	s_waitcnt lgkmcnt(6)
	v_cvt_pk_bf16_f32 v50, v58, v56
	s_waitcnt lgkmcnt(4)
	v_cvt_pk_bf16_f32 v51, v60, v62
	s_waitcnt lgkmcnt(2)
	v_cvt_pk_bf16_f32 v52, v64, v66
	s_waitcnt lgkmcnt(0)
	v_cvt_pk_bf16_f32 v53, v68, v70
	v_lshl_add_u64 v[54:55], v[72:73], 0, v[54:55]
	global_store_dwordx4 v[54:55], v[50:53], off
	v_or_b32_e32 v54, s16, v12
	v_ashrrev_i32_e32 v55, 31, v54
	v_cvt_pk_bf16_f32 v50, v59, v57
	v_cvt_pk_bf16_f32 v51, v61, v63
	v_cvt_pk_bf16_f32 v52, v65, v67
	v_cvt_pk_bf16_f32 v53, v69, v71
	v_lshlrev_b64 v[54:55], 12, v[54:55]
	ds_read2_b32 v[56:57], v9 offset0:16 offset1:20
	ds_read2_b32 v[58:59], v9 offset0:49 offset1:53
	ds_read2_b32 v[60:61], v9 offset0:82 offset1:86
	ds_read2_b32 v[62:63], v9 offset0:115 offset1:119
	ds_read2_b32 v[64:65], v9 offset0:148 offset1:152
	ds_read2_b32 v[66:67], v9 offset0:181 offset1:185
	ds_read2_b32 v[68:69], v9 offset0:214 offset1:218
	ds_read2_b32 v[70:71], v9 offset0:247 offset1:251
	v_lshl_add_u64 v[54:55], v[72:73], 0, v[54:55]
	global_store_dwordx4 v[54:55], v[50:53], off
	v_or_b32_e32 v54, s16, v13
	v_ashrrev_i32_e32 v55, 31, v54
	v_lshlrev_b64 v[54:55], 12, v[54:55]
	s_waitcnt lgkmcnt(6)
	v_cvt_pk_bf16_f32 v50, v56, v58
	s_waitcnt lgkmcnt(4)
	v_cvt_pk_bf16_f32 v51, v60, v62
	s_waitcnt lgkmcnt(2)
	v_cvt_pk_bf16_f32 v52, v64, v66
	s_waitcnt lgkmcnt(0)
	v_cvt_pk_bf16_f32 v53, v68, v70
	v_lshl_add_u64 v[54:55], v[72:73], 0, v[54:55]
	global_store_dwordx4 v[54:55], v[50:53], off
	v_or_b32_e32 v54, s16, v14
	v_ashrrev_i32_e32 v55, 31, v54
	v_cvt_pk_bf16_f32 v50, v57, v59
	v_cvt_pk_bf16_f32 v51, v61, v63
	v_cvt_pk_bf16_f32 v52, v65, v67
	v_cvt_pk_bf16_f32 v53, v69, v71
	v_lshlrev_b64 v[54:55], 12, v[54:55]
	ds_read2_b32 v[56:57], v9 offset0:24 offset1:28
	ds_read2_b32 v[58:59], v9 offset0:57 offset1:61
	ds_read2_b32 v[60:61], v9 offset0:90 offset1:94
	ds_read2_b32 v[62:63], v9 offset0:123 offset1:127
	ds_read2_b32 v[64:65], v9 offset0:156 offset1:160
	ds_read2_b32 v[66:67], v9 offset0:189 offset1:193
	ds_read2_b32 v[68:69], v9 offset0:222 offset1:226
	ds_read2_b32 v[70:71], v48 offset0:127 offset1:131
	v_lshl_add_u64 v[54:55], v[72:73], 0, v[54:55]
	global_store_dwordx4 v[54:55], v[50:53], off
	v_or_b32_e32 v54, s16, v15
	v_ashrrev_i32_e32 v55, 31, v54
	v_lshlrev_b64 v[54:55], 12, v[54:55]
	s_waitcnt lgkmcnt(6)
	v_cvt_pk_bf16_f32 v50, v56, v58
	s_waitcnt lgkmcnt(4)
	v_cvt_pk_bf16_f32 v51, v60, v62
	s_waitcnt lgkmcnt(2)
	v_cvt_pk_bf16_f32 v52, v64, v66
	s_waitcnt lgkmcnt(0)
	v_cvt_pk_bf16_f32 v53, v68, v70
	v_lshl_add_u64 v[54:55], v[72:73], 0, v[54:55]
	global_store_dwordx4 v[54:55], v[50:53], off
	v_or_b32_e32 v54, s16, v16
	v_ashrrev_i32_e32 v55, 31, v54
	v_lshlrev_b64 v[54:55], 12, v[54:55]
	v_cvt_pk_bf16_f32 v50, v57, v59
	v_cvt_pk_bf16_f32 v51, v61, v63
	v_cvt_pk_bf16_f32 v52, v65, v67
	v_cvt_pk_bf16_f32 v53, v69, v71
	v_lshl_add_u64 v[54:55], v[72:73], 0, v[54:55]
	global_store_dwordx4 v[54:55], v[50:53], off
	s_waitcnt lgkmcnt(0)
	s_branch .LBB0_16
